# LDS-read hoisting applied to all straight-line blocks of the token-mixing phases without incoming LDS dependencies (adds mLSTM conv sections)
# speedup vs baseline: 1.0105x; 1.0041x over previous
.LBB0_534:
	s_or_b64 exec, exec, s[14:15]
	s_waitcnt vmcnt(9)
	ds_write_b128 v146, v[72:75] offset:34816
	s_waitcnt vmcnt(8)
	ds_write_b128 v146, v[68:71] offset:34832
	s_mov_b64 s[14:15], exec
	v_readlane_b32 s16, v254, 47
	v_readlane_b32 s17, v254, 48
	s_and_b64 s[16:17], s[14:15], s[16:17]
	s_mov_b64 exec, s[16:17]
	ds_write_b128 v166, v[44:47] offset:54272
	s_or_b64 exec, exec, s[14:15]
	s_mov_b64 s[14:15], exec
	v_readlane_b32 s16, v254, 49
	v_readlane_b32 s17, v254, 50
	s_and_b64 s[16:17], s[14:15], s[16:17]
	s_mov_b64 exec, s[16:17]
	ds_write_b128 v167, v[40:43] offset:54272
	s_or_b64 exec, exec, s[14:15]
	s_mov_b64 s[14:15], exec
	v_readlane_b32 s16, v254, 51
	v_readlane_b32 s17, v254, 52
	s_and_b64 s[16:17], s[14:15], s[16:17]
	s_mov_b64 exec, s[16:17]
	ds_write_b128 v168, v[56:59] offset:54272
	s_or_b64 exec, exec, s[14:15]
	s_mov_b64 s[14:15], exec
	v_readlane_b32 s16, v254, 53
	v_readlane_b32 s17, v254, 54
	s_and_b64 s[16:17], s[14:15], s[16:17]
	s_mov_b64 exec, s[16:17]
	ds_write_b128 v169, v[48:51] offset:54272
	s_or_b64 exec, exec, s[14:15]
	s_and_saveexec_b64 s[14:15], s[58:59]
	ds_write_b128 v170, v[64:67] offset:54272
	s_or_b64 exec, exec, s[14:15]
	ds_read_b128 v[70:73], v147
	ds_read_b128 v[88:91], v147 offset:16
	ds_read_b128 v[132:135], v148
	ds_read_b128 v[182:185], v148 offset:16
	ds_read_b128 v[192:195], v148 offset:512
	ds_read_b128 v[196:199], v148 offset:528
	ds_read_b128 v[200:203], v148 offset:1024
	ds_read_b128 v[204:207], v148 offset:1040
	ds_read_b128 v[208:211], v148 offset:1536
	ds_read_b128 v[218:221], v148 offset:1552
	s_nop 0
	s_nop 0
	s_nop 0
	s_nop 0
	v_lshlrev_b32_e32 v64, 16, v52
	v_and_b32_e32 v65, 0xffff0000, v52
	v_lshlrev_b32_e32 v52, 16, v53
	v_and_b32_e32 v53, 0xffff0000, v53
	s_nop 0
	s_waitcnt lgkmcnt(7)
	v_pk_fma_f32 v[48:49], v[132:133], v[64:65], v[70:71]
	v_pk_fma_f32 v[50:51], v[134:135], v[52:53], v[72:73]
	v_lshlrev_b32_e32 v40, 16, v54
	v_and_b32_e32 v41, 0xffff0000, v54
	v_lshlrev_b32_e32 v42, 16, v55
	v_and_b32_e32 v43, 0xffff0000, v55
	s_nop 0
	s_waitcnt lgkmcnt(6)
	v_pk_fma_f32 v[52:53], v[182:183], v[40:41], v[88:89]
	v_pk_fma_f32 v[54:55], v[184:185], v[42:43], v[90:91]
	s_nop 0
	v_lshlrev_b32_e32 v40, 16, v60
	v_and_b32_e32 v41, 0xffff0000, v60
	v_lshlrev_b32_e32 v42, 16, v61
	v_and_b32_e32 v43, 0xffff0000, v61
	s_nop 0
	s_waitcnt lgkmcnt(5)
	v_pk_fma_f32 v[56:57], v[194:195], v[42:43], v[50:51]
	v_pk_fma_f32 v[58:59], v[192:193], v[40:41], v[48:49]
	s_nop 0
	v_lshlrev_b32_e32 v44, 16, v62
	v_and_b32_e32 v45, 0xffff0000, v62
	v_lshlrev_b32_e32 v46, 16, v63
	v_and_b32_e32 v47, 0xffff0000, v63
	s_nop 0
	s_waitcnt lgkmcnt(4)
	v_pk_fma_f32 v[60:61], v[198:199], v[46:47], v[54:55]
	v_pk_fma_f32 v[62:63], v[196:197], v[44:45], v[52:53]
	s_nop 0
	v_lshlrev_b32_e32 v48, 16, v36
	v_and_b32_e32 v49, 0xffff0000, v36
	v_lshlrev_b32_e32 v50, 16, v37
	v_and_b32_e32 v51, 0xffff0000, v37
	s_nop 0
	s_waitcnt lgkmcnt(3)
	v_pk_fma_f32 v[64:65], v[200:201], v[48:49], v[58:59]
	v_pk_fma_f32 v[66:67], v[202:203], v[50:51], v[56:57]
	s_nop 0
	v_lshlrev_b32_e32 v36, 16, v38
	v_and_b32_e32 v37, 0xffff0000, v38
	v_lshlrev_b32_e32 v38, 16, v39
	v_and_b32_e32 v39, 0xffff0000, v39
	s_nop 0
	s_waitcnt lgkmcnt(2)
	v_pk_fma_f32 v[68:69], v[206:207], v[38:39], v[60:61]
	s_nop 0
	v_lshlrev_b32_e32 v54, 16, v32
	v_and_b32_e32 v55, 0xffff0000, v32
	v_lshlrev_b32_e32 v56, 16, v33
	v_and_b32_e32 v57, 0xffff0000, v33
	s_nop 0
	s_waitcnt lgkmcnt(1)
	v_pk_fma_f32 v[66:67], v[210:211], v[56:57], v[66:67]
	v_pk_fma_f32 v[64:65], v[208:209], v[54:55], v[64:65]
	s_nop 0
	v_lshlrev_b32_e32 v32, 16, v35
	v_and_b32_e32 v33, 0xffff0000, v35
	v_pk_fma_f32 v[62:63], v[204:205], v[36:37], v[62:63]
	v_lshlrev_b32_e32 v52, 16, v34
	v_and_b32_e32 v53, 0xffff0000, v34
	s_nop 0
	s_waitcnt lgkmcnt(0)
	v_pk_fma_f32 v[34:35], v[220:221], v[32:33], v[68:69]
	v_mul_f32_e32 v60, 0xbfb8aa3b, v64
	v_mul_f32_e32 v61, 0xbfb8aa3b, v65
	v_exp_f32_e32 v60, v60
	v_exp_f32_e32 v61, v61
	v_pk_fma_f32 v[58:59], v[218:219], v[52:53], v[62:63]
	s_mov_b32 s14, 0x3db504f3
	v_add_f32_e32 v60, 1.0, v60
	v_add_f32_e32 v61, 1.0, v61
	v_rcp_f32_e32 v60, v60
	v_rcp_f32_e32 v61, v61
	v_mul_f32_e32 v62, 0xbfb8aa3b, v66
	v_mul_f32_e32 v63, 0xbfb8aa3b, v67
	v_exp_f32_e32 v62, v62
	v_pk_mul_f32 v[60:61], v[64:65], v[60:61]
	v_mul_f32_e32 v64, 0xbfb8aa3b, v58
	v_mul_f32_e32 v65, 0xbfb8aa3b, v59
	v_exp_f32_e32 v64, v64
	v_exp_f32_e32 v65, v65
	v_exp_f32_e32 v63, v63
	v_add_f32_e32 v62, 1.0, v62
	v_add_f32_e32 v64, 1.0, v64
	v_add_f32_e32 v65, 1.0, v65
	v_rcp_f32_e32 v64, v64
	v_rcp_f32_e32 v65, v65
	v_add_f32_e32 v63, 1.0, v63
	v_rcp_f32_e32 v62, v62
	v_rcp_f32_e32 v63, v63
	v_pk_mul_f32 v[58:59], v[58:59], v[64:65]
	v_pk_mul_f32 v[60:61], v[60:61], s[14:15] op_sel_hi:[1,0]
	v_pk_mul_f32 v[64:65], v[58:59], s[14:15] op_sel_hi:[1,0]
	v_mul_f32_e32 v58, 0xbfb8aa3b, v34
	v_mul_f32_e32 v59, 0xbfb8aa3b, v35
	v_exp_f32_e32 v58, v58
	v_exp_f32_e32 v59, v59
	v_pk_mul_f32 v[62:63], v[66:67], v[62:63]
	s_waitcnt lgkmcnt(0)
	s_and_b64 vcc, exec, s[12:13]
	v_add_f32_e32 v58, 1.0, v58
	v_add_f32_e32 v59, 1.0, v59
	v_rcp_f32_e32 v58, v58
	v_rcp_f32_e32 v59, v59
	v_pk_mul_f32 v[62:63], v[62:63], s[14:15] op_sel_hi:[1,0]
	v_pk_mul_f32 v[34:35], v[34:35], v[58:59]
	s_nop 0
	v_pk_mul_f32 v[34:35], v[34:35], s[14:15] op_sel_hi:[1,0]
	v_cvt_pk_bf16_f32 v58, v60, v61
	v_cvt_pk_bf16_f32 v59, v62, v63
	v_cvt_pk_bf16_f32 v60, v64, v65
	v_cvt_pk_bf16_f32 v61, v34, v35
	ds_write_b128 v171, v[58:61]
	ds_read_b128 v[88:91], v147
	ds_read_b128 v[132:135], v147 offset:16
	ds_read_b128 v[182:185], v148
	ds_read_b128 v[192:195], v148 offset:16
	ds_read_b128 v[196:199], v148 offset:512
	ds_read_b128 v[200:203], v148 offset:528
	ds_read_b128 v[204:207], v148 offset:1024
	ds_read_b128 v[208:211], v148 offset:1040
	ds_read_b128 v[218:221], v148 offset:1536
	ds_read_b128 v[240:243], v148 offset:1552
	s_nop 0
	s_nop 0
	s_nop 0
	s_nop 0
	s_nop 0
	s_waitcnt lgkmcnt(7)
	v_pk_fma_f32 v[34:35], v[182:183], v[40:41], v[88:89]
	v_pk_fma_f32 v[58:59], v[184:185], v[42:43], v[90:91]
	s_nop 0
	s_nop 0
	s_waitcnt lgkmcnt(6)
	v_pk_fma_f32 v[44:45], v[192:193], v[44:45], v[132:133]
	v_pk_fma_f32 v[46:47], v[194:195], v[46:47], v[134:135]
	s_nop 0
	s_waitcnt lgkmcnt(5)
	v_pk_fma_f32 v[50:51], v[198:199], v[50:51], v[58:59]
	v_pk_fma_f32 v[48:49], v[196:197], v[48:49], v[34:35]
	s_nop 0
	s_nop 0
	s_waitcnt lgkmcnt(4)
	v_pk_fma_f32 v[40:41], v[200:201], v[36:37], v[44:45]
	s_nop 0
	v_pk_fma_f32 v[38:39], v[202:203], v[38:39], v[46:47]
	s_nop 0
	s_waitcnt lgkmcnt(3)
	v_pk_fma_f32 v[42:43], v[204:205], v[54:55], v[48:49]
	v_pk_fma_f32 v[44:45], v[206:207], v[56:57], v[50:51]
	s_nop 0
	s_nop 0
	s_waitcnt lgkmcnt(2)
	v_pk_fma_f32 v[40:41], v[208:209], v[52:53], v[40:41]
	v_pk_fma_f32 v[36:37], v[210:211], v[32:33], v[38:39]
	s_nop 0
	v_lshlrev_b32_e32 v38, 16, v28
	v_and_b32_e32 v39, 0xffff0000, v28
	v_lshlrev_b32_e32 v28, 16, v29
	v_and_b32_e32 v29, 0xffff0000, v29
	s_nop 0
	s_waitcnt lgkmcnt(1)
	v_pk_fma_f32 v[34:35], v[220:221], v[28:29], v[44:45]
	v_pk_fma_f32 v[32:33], v[218:219], v[38:39], v[42:43]
	v_lshlrev_b32_e32 v38, 16, v30
	v_and_b32_e32 v39, 0xffff0000, v30
	v_lshlrev_b32_e32 v42, 16, v31
	v_and_b32_e32 v43, 0xffff0000, v31
	s_nop 0
	v_lshlrev_b32_e32 v44, 16, v24
	v_and_b32_e32 v45, 0xffff0000, v24
	v_lshlrev_b32_e32 v24, 16, v25
	v_and_b32_e32 v25, 0xffff0000, v25
	s_nop 0
	s_waitcnt lgkmcnt(0)
	v_pk_fma_f32 v[30:31], v[242:243], v[42:43], v[36:37]
	v_mul_f32_e32 v36, 0xbfb8aa3b, v32
	v_mul_f32_e32 v37, 0xbfb8aa3b, v33
	v_exp_f32_e32 v36, v36
	v_exp_f32_e32 v37, v37
	v_pk_fma_f32 v[28:29], v[240:241], v[38:39], v[40:41]
	v_add_f32_e32 v36, 1.0, v36
	v_add_f32_e32 v37, 1.0, v37
	v_rcp_f32_e32 v36, v36
	v_rcp_f32_e32 v37, v37
	s_nop 0
	v_pk_mul_f32 v[32:33], v[32:33], v[36:37]
	v_mul_f32_e32 v36, 0xbfb8aa3b, v34
	v_mul_f32_e32 v37, 0xbfb8aa3b, v35
	v_exp_f32_e32 v36, v36
	v_exp_f32_e32 v37, v37
	v_pk_mul_f32 v[32:33], v[32:33], s[14:15] op_sel_hi:[1,0]
	v_add_f32_e32 v36, 1.0, v36
	v_add_f32_e32 v37, 1.0, v37
	v_rcp_f32_e32 v36, v36
	v_rcp_f32_e32 v37, v37
	s_nop 0
	v_pk_mul_f32 v[34:35], v[34:35], v[36:37]
	v_mul_f32_e32 v36, 0xbfb8aa3b, v28
	v_mul_f32_e32 v37, 0xbfb8aa3b, v29
	v_exp_f32_e32 v36, v36
	v_exp_f32_e32 v37, v37
	v_pk_mul_f32 v[34:35], v[34:35], s[14:15] op_sel_hi:[1,0]
	v_add_f32_e32 v36, 1.0, v36
	v_add_f32_e32 v37, 1.0, v37
	v_rcp_f32_e32 v36, v36
	v_rcp_f32_e32 v37, v37
	s_nop 0
	v_pk_mul_f32 v[28:29], v[28:29], v[36:37]
	s_nop 0
	v_pk_mul_f32 v[36:37], v[28:29], s[14:15] op_sel_hi:[1,0]
	v_mul_f32_e32 v28, 0xbfb8aa3b, v30
	v_mul_f32_e32 v29, 0xbfb8aa3b, v31
	v_exp_f32_e32 v28, v28
	v_exp_f32_e32 v29, v29
	v_add_f32_e32 v28, 1.0, v28
	v_add_f32_e32 v29, 1.0, v29
	v_rcp_f32_e32 v28, v28
	v_rcp_f32_e32 v29, v29
	s_nop 0
	v_pk_mul_f32 v[28:29], v[30:31], v[28:29]
	s_nop 0
	v_pk_mul_f32 v[38:39], v[28:29], s[14:15] op_sel_hi:[1,0]
	v_cvt_pk_bf16_f32 v28, v32, v33
	v_cvt_pk_bf16_f32 v29, v34, v35
	v_cvt_pk_bf16_f32 v30, v36, v37
	v_cvt_pk_bf16_f32 v31, v38, v39
	ds_write_b128 v171, v[28:31] offset:272
	ds_read_b128 v[88:91], v147 offset:512
	ds_read_b128 v[182:185], v147 offset:528
	ds_read_b128 v[132:135], v148 offset:2048
	ds_read_b128 v[192:195], v148 offset:2064
	ds_read_b128 v[196:199], v148 offset:2560
	ds_read_b128 v[200:203], v148 offset:2576
	ds_read_b128 v[204:207], v148 offset:3072
	ds_read_b128 v[208:211], v148 offset:3088
	ds_read_b128 v[218:221], v148 offset:3584
	ds_read_b128 v[240:243], v148 offset:3600
	s_nop 0
	s_nop 0
	s_nop 0
	s_nop 0
	s_nop 0
	s_waitcnt lgkmcnt(7)
	v_pk_fma_f32 v[30:31], v[134:135], v[24:25], v[90:91]
	v_lshlrev_b32_e32 v24, 16, v26
	v_and_b32_e32 v25, 0xffff0000, v26
	v_lshlrev_b32_e32 v26, 16, v27
	v_and_b32_e32 v27, 0xffff0000, v27
	v_pk_fma_f32 v[36:37], v[132:133], v[44:45], v[88:89]
	s_nop 0
	s_waitcnt lgkmcnt(6)
	v_pk_fma_f32 v[34:35], v[194:195], v[26:27], v[184:185]
	s_nop 0
	v_pk_fma_f32 v[32:33], v[192:193], v[24:25], v[182:183]
	v_lshlrev_b32_e32 v24, 16, v20
	v_and_b32_e32 v25, 0xffff0000, v20
	v_lshlrev_b32_e32 v20, 16, v21
	v_and_b32_e32 v21, 0xffff0000, v21
	s_nop 0
	s_waitcnt lgkmcnt(5)
	v_pk_fma_f32 v[38:39], v[198:199], v[20:21], v[30:31]
	s_nop 0
	v_pk_fma_f32 v[36:37], v[196:197], v[24:25], v[36:37]
	v_lshlrev_b32_e32 v26, 16, v22
	v_and_b32_e32 v27, 0xffff0000, v22
	v_lshlrev_b32_e32 v22, 16, v23
	v_and_b32_e32 v23, 0xffff0000, v23
	s_nop 0
	s_waitcnt lgkmcnt(4)
	v_pk_fma_f32 v[40:41], v[202:203], v[22:23], v[34:35]
	v_pk_fma_f32 v[42:43], v[200:201], v[26:27], v[32:33]
	s_nop 0
	v_lshlrev_b32_e32 v28, 16, v16
	v_and_b32_e32 v29, 0xffff0000, v16
	v_lshlrev_b32_e32 v30, 16, v17
	v_and_b32_e32 v31, 0xffff0000, v17
	s_nop 0
	s_waitcnt lgkmcnt(3)
	v_pk_fma_f32 v[44:45], v[204:205], v[28:29], v[36:37]
	v_pk_fma_f32 v[46:47], v[206:207], v[30:31], v[38:39]
	s_nop 0
	v_lshlrev_b32_e32 v16, 16, v18
	v_and_b32_e32 v17, 0xffff0000, v18
	v_lshlrev_b32_e32 v18, 16, v19
	v_and_b32_e32 v19, 0xffff0000, v19
	s_nop 0
	s_waitcnt lgkmcnt(2)
	v_pk_fma_f32 v[48:49], v[210:211], v[18:19], v[40:41]
	s_nop 0
	v_lshlrev_b32_e32 v34, 16, v12
	v_and_b32_e32 v35, 0xffff0000, v12
	v_lshlrev_b32_e32 v36, 16, v13
	v_and_b32_e32 v37, 0xffff0000, v13
	s_nop 0
	s_waitcnt lgkmcnt(1)
	v_pk_fma_f32 v[46:47], v[220:221], v[36:37], v[46:47]
	v_pk_fma_f32 v[44:45], v[218:219], v[34:35], v[44:45]
	s_nop 0
	v_lshlrev_b32_e32 v12, 16, v15
	v_and_b32_e32 v13, 0xffff0000, v15
	v_pk_fma_f32 v[42:43], v[208:209], v[16:17], v[42:43]
	v_lshlrev_b32_e32 v32, 16, v14
	v_and_b32_e32 v33, 0xffff0000, v14
	s_nop 0
	s_waitcnt lgkmcnt(0)
	v_pk_fma_f32 v[14:15], v[242:243], v[12:13], v[48:49]
	v_mul_f32_e32 v40, 0xbfb8aa3b, v44
	v_mul_f32_e32 v41, 0xbfb8aa3b, v45
	v_exp_f32_e32 v40, v40
	v_exp_f32_e32 v41, v41
	v_pk_fma_f32 v[38:39], v[240:241], v[32:33], v[42:43]
	v_mul_f32_e32 v42, 0xbfb8aa3b, v46
	v_add_f32_e32 v40, 1.0, v40
	v_add_f32_e32 v41, 1.0, v41
	v_rcp_f32_e32 v40, v40
	v_rcp_f32_e32 v41, v41
	v_mul_f32_e32 v43, 0xbfb8aa3b, v47
	v_exp_f32_e32 v42, v42
	v_exp_f32_e32 v43, v43
	v_pk_mul_f32 v[40:41], v[44:45], v[40:41]
	v_mul_f32_e32 v44, 0xbfb8aa3b, v38
	v_mul_f32_e32 v45, 0xbfb8aa3b, v39
	v_exp_f32_e32 v44, v44
	v_exp_f32_e32 v45, v45
	v_add_f32_e32 v42, 1.0, v42
	v_add_f32_e32 v43, 1.0, v43
	v_add_f32_e32 v44, 1.0, v44
	v_add_f32_e32 v45, 1.0, v45
	v_rcp_f32_e32 v44, v44
	v_rcp_f32_e32 v45, v45
	v_rcp_f32_e32 v42, v42
	v_rcp_f32_e32 v43, v43
	v_pk_mul_f32 v[44:45], v[38:39], v[44:45]
	v_mul_f32_e32 v38, 0xbfb8aa3b, v14
	v_mul_f32_e32 v39, 0xbfb8aa3b, v15
	v_exp_f32_e32 v38, v38
	v_exp_f32_e32 v39, v39
	v_pk_mul_f32 v[42:43], v[46:47], v[42:43]
	v_add_f32_e32 v38, 1.0, v38
	v_add_f32_e32 v39, 1.0, v39
	v_rcp_f32_e32 v38, v38
	v_rcp_f32_e32 v39, v39
	s_nop 0
	v_pk_mul_f32 v[14:15], v[14:15], v[38:39]
	v_cvt_pk_bf16_f32 v38, v40, v41
	v_cvt_pk_bf16_f32 v39, v42, v43
	v_cvt_pk_bf16_f32 v40, v44, v45
	v_cvt_pk_bf16_f32 v41, v14, v15
	ds_write_b128 v171, v[38:41] offset:17408
	ds_read_b128 v[88:91], v147 offset:512
	ds_read_b128 v[132:135], v147 offset:528
	ds_read_b128 v[182:185], v148 offset:2048
	ds_read_b128 v[192:195], v148 offset:2064
	ds_read_b128 v[196:199], v148 offset:2560
	ds_read_b128 v[200:203], v148 offset:2576
	ds_read_b128 v[204:207], v148 offset:3072
	ds_read_b128 v[218:221], v148 offset:3088
	ds_read_b128 v[208:211], v148 offset:3584
	ds_read_b128 v[240:243], v148 offset:3600
	s_nop 0
	s_nop 0
	s_nop 0
	s_nop 0
	s_nop 0
	s_waitcnt lgkmcnt(7)
	v_pk_fma_f32 v[14:15], v[182:183], v[24:25], v[88:89]
	v_pk_fma_f32 v[24:25], v[184:185], v[20:21], v[90:91]
	s_nop 0
	s_waitcnt lgkmcnt(6)
	v_pk_fma_f32 v[38:39], v[194:195], v[22:23], v[134:135]
	s_nop 0
	v_pk_fma_f32 v[26:27], v[192:193], v[26:27], v[132:133]
	s_nop 0
	s_waitcnt lgkmcnt(5)
	v_pk_fma_f32 v[24:25], v[198:199], v[30:31], v[24:25]
	v_pk_fma_f32 v[28:29], v[196:197], v[28:29], v[14:15]
	s_nop 0
	s_nop 0
	s_waitcnt lgkmcnt(4)
	v_pk_fma_f32 v[20:21], v[200:201], v[16:17], v[26:27]
	s_nop 0
	v_pk_fma_f32 v[18:19], v[202:203], v[18:19], v[38:39]
	s_nop 0
	s_waitcnt lgkmcnt(3)
	v_pk_fma_f32 v[22:23], v[204:205], v[34:35], v[28:29]
	v_pk_fma_f32 v[24:25], v[206:207], v[36:37], v[24:25]
	s_nop 0
	s_nop 0
	s_waitcnt lgkmcnt(2)
	v_pk_fma_f32 v[20:21], v[218:219], v[32:33], v[20:21]
	v_pk_fma_f32 v[16:17], v[220:221], v[12:13], v[18:19]
	s_nop 0
	v_lshlrev_b32_e32 v18, 16, v8
	v_and_b32_e32 v19, 0xffff0000, v8
	v_lshlrev_b32_e32 v8, 16, v9
	v_and_b32_e32 v9, 0xffff0000, v9
	s_nop 0
	s_waitcnt lgkmcnt(1)
	v_pk_fma_f32 v[14:15], v[210:211], v[8:9], v[24:25]
	v_pk_fma_f32 v[12:13], v[208:209], v[18:19], v[22:23]
	v_lshlrev_b32_e32 v18, 16, v10
	v_and_b32_e32 v19, 0xffff0000, v10
	v_lshlrev_b32_e32 v22, 16, v11
	v_and_b32_e32 v23, 0xffff0000, v11
	s_nop 0
	s_nop 0
	s_waitcnt lgkmcnt(0)
	v_pk_fma_f32 v[10:11], v[242:243], v[22:23], v[16:17]
	v_mul_f32_e32 v16, 0xbfb8aa3b, v12
	v_mul_f32_e32 v17, 0xbfb8aa3b, v13
	v_exp_f32_e32 v16, v16
	v_exp_f32_e32 v17, v17
	v_pk_fma_f32 v[8:9], v[240:241], v[18:19], v[20:21]
	v_add_f32_e32 v16, 1.0, v16
	v_add_f32_e32 v17, 1.0, v17
	v_rcp_f32_e32 v16, v16
	v_rcp_f32_e32 v17, v17
	s_nop 0
	v_pk_mul_f32 v[12:13], v[12:13], v[16:17]
	v_mul_f32_e32 v16, 0xbfb8aa3b, v14
	v_mul_f32_e32 v17, 0xbfb8aa3b, v15
	v_exp_f32_e32 v16, v16
	v_exp_f32_e32 v17, v17
	v_add_f32_e32 v16, 1.0, v16
	v_add_f32_e32 v17, 1.0, v17
	v_rcp_f32_e32 v16, v16
	v_rcp_f32_e32 v17, v17
	s_nop 0
	v_pk_mul_f32 v[14:15], v[14:15], v[16:17]
	v_mul_f32_e32 v16, 0xbfb8aa3b, v8
	v_mul_f32_e32 v17, 0xbfb8aa3b, v9
	v_exp_f32_e32 v16, v16
	v_exp_f32_e32 v17, v17
	v_add_f32_e32 v16, 1.0, v16
	v_add_f32_e32 v17, 1.0, v17
	v_rcp_f32_e32 v16, v16
	v_rcp_f32_e32 v17, v17
	s_nop 0
	v_pk_mul_f32 v[16:17], v[8:9], v[16:17]
	v_mul_f32_e32 v8, 0xbfb8aa3b, v10
	v_mul_f32_e32 v9, 0xbfb8aa3b, v11
	v_exp_f32_e32 v8, v8
	v_exp_f32_e32 v9, v9
	v_add_f32_e32 v8, 1.0, v8
	v_add_f32_e32 v9, 1.0, v9
	v_rcp_f32_e32 v8, v8
	v_rcp_f32_e32 v9, v9
	s_nop 0
	v_pk_mul_f32 v[18:19], v[10:11], v[8:9]
	v_cvt_pk_bf16_f32 v8, v12, v13
	v_cvt_pk_bf16_f32 v9, v14, v15
	v_cvt_pk_bf16_f32 v10, v16, v17
	v_cvt_pk_bf16_f32 v11, v18, v19
	ds_write_b128 v171, v[8:11] offset:17680
	s_waitcnt lgkmcnt(0)
	s_cbranch_vccnz .LBB0_546
	v_and_b32_e32 v8, 64, v216
	v_add_u32_e32 v9, -1, v216
	v_cmp_lt_i32_e32 vcc, v9, v8
	v_add_u32_e32 v11, -2, v216
	v_readlane_b32 s12, v254, 57
	v_cndmask_b32_e32 v9, v9, v216, vcc
	v_lshlrev_b32_e32 v9, 2, v9
	ds_bpermute_b32 v10, v9, v77
	v_cmp_lt_i32_e32 vcc, v11, v8
	v_readlane_b32 s13, v254, 58
	v_readlane_b32 s14, v254, 59
	v_cndmask_b32_e32 v11, v11, v216, vcc
	s_waitcnt lgkmcnt(0)
	v_add_f32_e32 v10, v77, v10
	v_cndmask_b32_e64 v10, v10, v77, s[48:49]
	v_lshlrev_b32_e32 v11, 2, v11
	ds_bpermute_b32 v12, v11, v10
	v_readlane_b32 s15, v254, 60
	v_readlane_b32 s16, v254, 61
	v_readlane_b32 s17, v254, 62
	v_readlane_b32 s18, v254, 63
	s_waitcnt lgkmcnt(0)
	v_add_f32_e32 v12, v10, v12
	v_cndmask_b32_e64 v10, v12, v10, s[12:13]
	v_add_u32_e32 v12, -4, v216
	v_cmp_lt_i32_e32 vcc, v12, v8
	v_readlane_b32 s19, v255, 0
	s_ashr_i32 s9, s8, 31
	v_cndmask_b32_e32 v12, v12, v216, vcc
	v_lshlrev_b32_e32 v12, 2, v12
	ds_bpermute_b32 v13, v12, v10
	s_waitcnt lgkmcnt(0)
	v_add_f32_e32 v13, v10, v13
	v_cndmask_b32_e64 v10, v13, v10, s[14:15]
	v_add_u32_e32 v13, -8, v216
	v_cmp_lt_i32_e32 vcc, v13, v8
	s_nop 1
	v_cndmask_b32_e32 v13, v13, v216, vcc
	v_lshlrev_b32_e32 v13, 2, v13
	ds_bpermute_b32 v14, v13, v10
	s_waitcnt lgkmcnt(0)
	v_add_f32_e32 v14, v10, v14
	v_cndmask_b32_e64 v10, v14, v10, s[16:17]
	v_add_u32_e32 v14, -16, v216
	v_cmp_lt_i32_e32 vcc, v14, v8
	s_nop 1
	v_cndmask_b32_e32 v14, v14, v216, vcc
	v_lshlrev_b32_e32 v14, 2, v14
	ds_bpermute_b32 v15, v14, v10
	s_waitcnt lgkmcnt(0)
	v_add_f32_e32 v15, v10, v15
	v_cndmask_b32_e64 v10, v15, v10, s[68:69]
	v_subrev_u32_e32 v15, 32, v216
	v_cmp_lt_i32_e32 vcc, v15, v8
	s_nop 1
	v_cndmask_b32_e32 v8, v15, v216, vcc
	v_lshlrev_b32_e32 v8, 2, v8
	ds_bpermute_b32 v15, v8, v10
	s_waitcnt lgkmcnt(0)
	v_add_f32_e32 v15, v10, v15
	v_cndmask_b32_e64 v10, v15, v10, s[18:19]
	v_sub_f32_e32 v15, v76, v10
	ds_bpermute_b32 v9, v9, v15
	ds_write2st64_b32 v149, v10, v15 offset1:1
	s_waitcnt lgkmcnt(1)
	v_max_f32_e32 v9, v9, v9
	v_max_f32_e32 v9, v15, v9
	v_cndmask_b32_e64 v9, v9, v15, s[48:49]
	ds_bpermute_b32 v11, v11, v9
	s_waitcnt lgkmcnt(0)
	v_max_f32_e32 v11, v11, v11
	v_max_f32_e32 v11, v9, v11
	v_cndmask_b32_e64 v9, v11, v9, s[12:13]
	ds_bpermute_b32 v11, v12, v9
	s_lshl_b64 s[12:13], s[8:9], 2
	v_readlane_b32 s9, v251, 53
	s_add_u32 s12, s9, s12
	v_readlane_b32 s9, v251, 54
	s_waitcnt lgkmcnt(0)
	v_max_f32_e32 v11, v11, v11
	v_max_f32_e32 v11, v9, v11
	v_cndmask_b32_e64 v9, v11, v9, s[14:15]
	ds_bpermute_b32 v11, v13, v9
	s_addc_u32 s13, s9, s13
	s_waitcnt lgkmcnt(0)
	v_max_f32_e32 v11, v11, v11
	v_max_f32_e32 v11, v9, v11
	v_cndmask_b32_e64 v9, v11, v9, s[16:17]
	ds_bpermute_b32 v11, v14, v9
	s_waitcnt lgkmcnt(0)
	v_max_f32_e32 v11, v11, v11
	v_max_f32_e32 v11, v9, v11
	v_cndmask_b32_e64 v9, v11, v9, s[68:69]
	ds_bpermute_b32 v8, v8, v9
	v_max_f32_e32 v11, v9, v9
	s_waitcnt lgkmcnt(0)
	v_max_f32_e32 v8, v8, v8
	v_max_f32_e32 v8, v11, v8
	v_cndmask_b32_e64 v8, v8, v9, s[18:19]
	global_load_dword v9, v181, s[12:13]
	v_max_f32_e32 v8, v8, v8
	s_waitcnt vmcnt(0)
	v_max_f32_e32 v11, v9, v9
	v_max_f32_e32 v8, v8, v11
	v_add_f32_e32 v8, v10, v8
	v_add_f32_e32 v9, v9, v10
	v_sub_f32_e32 v9, v9, v8
	v_mul_f32_e32 v9, 0x3fb8aa3b, v9
	v_exp_f32_e32 v9, v9
	ds_write2st64_b32 v149, v8, v9 offset0:2 offset1:3
	v_mul_f32_e32 v8, 0xbfb8aa3b, v8
	v_exp_f32_e32 v8, v8
	ds_write_b32 v149, v8 offset:1280

.LBB0_566:
	s_or_b64 exec, exec, s[14:15]
	s_waitcnt vmcnt(1)
	ds_write_b128 v146, v[32:35] offset:34816
	s_waitcnt vmcnt(0)
	ds_write_b128 v146, v[28:31] offset:34832
	ds_read_b128 v[28:31], v161
	ds_read_b128 v[32:35], v161 offset:16
	ds_read_b128 v[40:43], v162
	s_waitcnt lgkmcnt(6)
	ds_read_b128 v[44:47], v162 offset:16
	v_lshlrev_b32_e32 v36, 16, v24
	v_and_b32_e32 v37, 0xffff0000, v24
	v_lshlrev_b32_e32 v24, 16, v25
	v_and_b32_e32 v25, 0xffff0000, v25
	s_waitcnt lgkmcnt(1)
	v_pk_fma_f32 v[30:31], v[42:43], v[24:25], v[30:31]
	v_lshlrev_b32_e32 v24, 16, v26
	v_and_b32_e32 v25, 0xffff0000, v26
	v_lshlrev_b32_e32 v26, 16, v27
	v_and_b32_e32 v27, 0xffff0000, v27
	v_pk_fma_f32 v[36:37], v[40:41], v[36:37], v[28:29]
	s_waitcnt lgkmcnt(0)
	v_pk_fma_f32 v[34:35], v[46:47], v[26:27], v[34:35]
	ds_read_b128 v[26:29], v162 offset:512
	v_pk_fma_f32 v[32:33], v[44:45], v[24:25], v[32:33]
	v_lshlrev_b32_e32 v24, 16, v20
	v_and_b32_e32 v25, 0xffff0000, v20
	v_lshlrev_b32_e32 v20, 16, v21
	v_and_b32_e32 v21, 0xffff0000, v21
	s_waitcnt lgkmcnt(0)
	v_pk_fma_f32 v[40:41], v[28:29], v[20:21], v[30:31]
	ds_read_b128 v[28:31], v162 offset:528
	v_pk_fma_f32 v[36:37], v[26:27], v[24:25], v[36:37]
	v_lshlrev_b32_e32 v26, 16, v22
	v_and_b32_e32 v27, 0xffff0000, v22
	v_lshlrev_b32_e32 v22, 16, v23
	v_and_b32_e32 v23, 0xffff0000, v23
	s_waitcnt lgkmcnt(0)
	v_pk_fma_f32 v[42:43], v[30:31], v[22:23], v[34:35]
	v_pk_fma_f32 v[44:45], v[28:29], v[26:27], v[32:33]
	ds_read_b128 v[32:35], v162 offset:1024
	v_lshlrev_b32_e32 v28, 16, v16
	v_and_b32_e32 v29, 0xffff0000, v16
	v_lshlrev_b32_e32 v30, 16, v17
	v_and_b32_e32 v31, 0xffff0000, v17
	s_waitcnt lgkmcnt(0)
	v_pk_fma_f32 v[46:47], v[32:33], v[28:29], v[36:37]
	v_pk_fma_f32 v[48:49], v[34:35], v[30:31], v[40:41]
	ds_read_b128 v[32:35], v162 offset:1040
	v_lshlrev_b32_e32 v16, 16, v18
	v_and_b32_e32 v17, 0xffff0000, v18
	v_lshlrev_b32_e32 v18, 16, v19
	v_and_b32_e32 v19, 0xffff0000, v19
	s_waitcnt lgkmcnt(0)
	v_pk_fma_f32 v[50:51], v[34:35], v[18:19], v[42:43]
	ds_read_b128 v[40:43], v162 offset:1536
	v_lshlrev_b32_e32 v34, 16, v12
	v_and_b32_e32 v35, 0xffff0000, v12
	v_lshlrev_b32_e32 v36, 16, v13
	v_and_b32_e32 v37, 0xffff0000, v13
	s_waitcnt lgkmcnt(0)
	v_pk_fma_f32 v[48:49], v[42:43], v[36:37], v[48:49]
	v_pk_fma_f32 v[46:47], v[40:41], v[34:35], v[46:47]
	ds_read_b128 v[40:43], v162 offset:1552
	v_lshlrev_b32_e32 v12, 16, v15
	v_and_b32_e32 v13, 0xffff0000, v15
	v_pk_fma_f32 v[44:45], v[32:33], v[16:17], v[44:45]
	v_lshlrev_b32_e32 v32, 16, v14
	v_and_b32_e32 v33, 0xffff0000, v14
	s_waitcnt lgkmcnt(0)
	v_pk_fma_f32 v[14:15], v[42:43], v[12:13], v[50:51]
	v_mul_f32_e32 v42, 0xbfb8aa3b, v46
	v_mul_f32_e32 v43, 0xbfb8aa3b, v47
	v_exp_f32_e32 v42, v42
	v_exp_f32_e32 v43, v43
	v_pk_fma_f32 v[40:41], v[40:41], v[32:33], v[44:45]
	v_mul_f32_e32 v44, 0xbfb8aa3b, v48
	v_add_f32_e32 v42, 1.0, v42
	v_add_f32_e32 v43, 1.0, v43
	v_rcp_f32_e32 v42, v42
	v_rcp_f32_e32 v43, v43
	v_mul_f32_e32 v45, 0xbfb8aa3b, v49
	v_exp_f32_e32 v44, v44
	v_exp_f32_e32 v45, v45
	v_pk_mul_f32 v[42:43], v[46:47], v[42:43]
	v_mul_f32_e32 v46, 0xbfb8aa3b, v40
	v_mul_f32_e32 v47, 0xbfb8aa3b, v41
	v_exp_f32_e32 v46, v46
	v_exp_f32_e32 v47, v47
	v_add_f32_e32 v44, 1.0, v44
	v_add_f32_e32 v45, 1.0, v45
	v_add_f32_e32 v46, 1.0, v46
	v_add_f32_e32 v47, 1.0, v47
	v_rcp_f32_e32 v46, v46
	v_rcp_f32_e32 v47, v47
	v_rcp_f32_e32 v44, v44
	v_rcp_f32_e32 v45, v45
	s_and_b64 vcc, exec, s[12:13]
	v_pk_mul_f32 v[46:47], v[40:41], v[46:47]
	v_mul_f32_e32 v40, 0xbfb8aa3b, v14
	v_mul_f32_e32 v41, 0xbfb8aa3b, v15
	v_exp_f32_e32 v40, v40
	v_exp_f32_e32 v41, v41
	v_pk_mul_f32 v[44:45], v[48:49], v[44:45]
	v_add_f32_e32 v40, 1.0, v40
	v_add_f32_e32 v41, 1.0, v41
	v_rcp_f32_e32 v40, v40
	v_rcp_f32_e32 v41, v41
	s_nop 0
	v_pk_mul_f32 v[14:15], v[14:15], v[40:41]
	v_cvt_pk_bf16_f32 v40, v42, v43
	v_cvt_pk_bf16_f32 v41, v44, v45
	v_cvt_pk_bf16_f32 v42, v46, v47
	v_cvt_pk_bf16_f32 v43, v14, v15
	ds_write_b128 v177, v[40:43] offset:17408
	ds_read_b128 v[56:59], v161
	ds_read_b128 v[60:63], v161 offset:16
	ds_read_b128 v[64:67], v162
	ds_read_b128 v[68:71], v162 offset:16
	ds_read_b128 v[72:75], v162 offset:512
	ds_read_b128 v[76:79], v162 offset:528
	ds_read_b128 v[88:91], v162 offset:1024
	ds_read_b128 v[132:135], v162 offset:1040
	ds_read_b128 v[182:185], v162 offset:1536
	ds_read_b128 v[192:195], v162 offset:1552
	s_nop 0
	s_nop 0
	s_nop 0
	s_nop 0
	s_nop 0
	s_waitcnt lgkmcnt(7)
	v_pk_fma_f32 v[14:15], v[64:65], v[24:25], v[56:57]
	v_pk_fma_f32 v[24:25], v[66:67], v[20:21], v[58:59]
	s_nop 0
	s_waitcnt lgkmcnt(6)
	v_pk_fma_f32 v[40:41], v[70:71], v[22:23], v[62:63]
	s_nop 0
	v_pk_fma_f32 v[26:27], v[68:69], v[26:27], v[60:61]
	s_nop 0
	s_waitcnt lgkmcnt(5)
	v_pk_fma_f32 v[24:25], v[74:75], v[30:31], v[24:25]
	v_pk_fma_f32 v[28:29], v[72:73], v[28:29], v[14:15]
	s_nop 0
	s_nop 0
	s_waitcnt lgkmcnt(4)
	v_pk_fma_f32 v[20:21], v[76:77], v[16:17], v[26:27]
	s_nop 0
	v_pk_fma_f32 v[18:19], v[78:79], v[18:19], v[40:41]
	s_nop 0
	s_waitcnt lgkmcnt(3)
	v_pk_fma_f32 v[22:23], v[88:89], v[34:35], v[28:29]
	v_pk_fma_f32 v[24:25], v[90:91], v[36:37], v[24:25]
	s_nop 0
	s_nop 0
	s_waitcnt lgkmcnt(2)
	v_pk_fma_f32 v[20:21], v[132:133], v[32:33], v[20:21]
	v_pk_fma_f32 v[16:17], v[134:135], v[12:13], v[18:19]
	s_nop 0
	v_lshlrev_b32_e32 v18, 16, v8
	v_and_b32_e32 v19, 0xffff0000, v8
	v_lshlrev_b32_e32 v8, 16, v9
	v_and_b32_e32 v9, 0xffff0000, v9
	s_nop 0
	s_waitcnt lgkmcnt(1)
	v_pk_fma_f32 v[14:15], v[184:185], v[8:9], v[24:25]
	v_pk_fma_f32 v[12:13], v[182:183], v[18:19], v[22:23]
	v_lshlrev_b32_e32 v18, 16, v10
	v_and_b32_e32 v19, 0xffff0000, v10
	v_lshlrev_b32_e32 v22, 16, v11
	v_and_b32_e32 v23, 0xffff0000, v11
	s_nop 0
	s_nop 0
	s_waitcnt lgkmcnt(0)
	v_pk_fma_f32 v[10:11], v[194:195], v[22:23], v[16:17]
	v_mul_f32_e32 v16, 0xbfb8aa3b, v12
	v_mul_f32_e32 v17, 0xbfb8aa3b, v13
	v_exp_f32_e32 v16, v16
	v_exp_f32_e32 v17, v17
	v_pk_fma_f32 v[8:9], v[192:193], v[18:19], v[20:21]
	v_add_f32_e32 v16, 1.0, v16
	v_add_f32_e32 v17, 1.0, v17
	v_rcp_f32_e32 v16, v16
	v_rcp_f32_e32 v17, v17
	s_nop 0
	v_pk_mul_f32 v[12:13], v[12:13], v[16:17]
	v_mul_f32_e32 v16, 0xbfb8aa3b, v14
	v_mul_f32_e32 v17, 0xbfb8aa3b, v15
	v_exp_f32_e32 v16, v16
	v_exp_f32_e32 v17, v17
	v_add_f32_e32 v16, 1.0, v16
	v_add_f32_e32 v17, 1.0, v17
	v_rcp_f32_e32 v16, v16
	v_rcp_f32_e32 v17, v17
	s_nop 0
	v_pk_mul_f32 v[14:15], v[14:15], v[16:17]
	v_mul_f32_e32 v16, 0xbfb8aa3b, v8
	v_mul_f32_e32 v17, 0xbfb8aa3b, v9
	v_exp_f32_e32 v16, v16
	v_exp_f32_e32 v17, v17
	v_add_f32_e32 v16, 1.0, v16
	v_add_f32_e32 v17, 1.0, v17
	v_rcp_f32_e32 v16, v16
	v_rcp_f32_e32 v17, v17
	s_nop 0
	v_pk_mul_f32 v[16:17], v[8:9], v[16:17]
	v_mul_f32_e32 v8, 0xbfb8aa3b, v10
	v_mul_f32_e32 v9, 0xbfb8aa3b, v11
	v_exp_f32_e32 v8, v8
	v_exp_f32_e32 v9, v9
	v_add_f32_e32 v8, 1.0, v8
	v_add_f32_e32 v9, 1.0, v9
	v_rcp_f32_e32 v8, v8
	v_rcp_f32_e32 v9, v9
	s_nop 0
	v_pk_mul_f32 v[18:19], v[10:11], v[8:9]
	v_cvt_pk_bf16_f32 v8, v12, v13
	v_cvt_pk_bf16_f32 v9, v14, v15
	v_cvt_pk_bf16_f32 v10, v16, v17
	v_cvt_pk_bf16_f32 v11, v18, v19
	ds_write_b128 v178, v[8:11] offset:17408
	s_waitcnt lgkmcnt(0)
	s_cbranch_vccnz .LBB0_570
	v_and_b32_e32 v8, 64, v216
	v_add_u32_e32 v9, -1, v216
	v_cmp_lt_i32_e32 vcc, v9, v8
	v_add_u32_e32 v11, -2, v216
	v_readlane_b32 s12, v254, 57
	v_cndmask_b32_e32 v9, v9, v216, vcc
	v_lshlrev_b32_e32 v9, 2, v9
	ds_bpermute_b32 v10, v9, v39
	v_cmp_lt_i32_e32 vcc, v11, v8
	v_readlane_b32 s13, v254, 58
	v_readlane_b32 s14, v254, 59
	v_cndmask_b32_e32 v11, v11, v216, vcc
	s_waitcnt lgkmcnt(0)
	v_add_f32_e32 v10, v39, v10
	v_cndmask_b32_e64 v10, v10, v39, s[48:49]
	v_lshlrev_b32_e32 v11, 2, v11
	ds_bpermute_b32 v12, v11, v10
	v_readlane_b32 s15, v254, 60
	v_readlane_b32 s16, v254, 61
	v_readlane_b32 s17, v254, 62
	v_readlane_b32 s18, v254, 63
	s_waitcnt lgkmcnt(0)
	v_add_f32_e32 v12, v10, v12
	v_cndmask_b32_e64 v10, v12, v10, s[12:13]
	v_add_u32_e32 v12, -4, v216
	v_cmp_lt_i32_e32 vcc, v12, v8
	v_readlane_b32 s19, v255, 0
	s_nop 0
	v_cndmask_b32_e32 v12, v12, v216, vcc
	v_lshlrev_b32_e32 v12, 2, v12
	ds_bpermute_b32 v13, v12, v10
	s_waitcnt lgkmcnt(0)
	v_add_f32_e32 v13, v10, v13
	v_cndmask_b32_e64 v10, v13, v10, s[14:15]
	v_add_u32_e32 v13, -8, v216
	v_cmp_lt_i32_e32 vcc, v13, v8
	s_nop 1
	v_cndmask_b32_e32 v13, v13, v216, vcc
	v_lshlrev_b32_e32 v13, 2, v13
	ds_bpermute_b32 v14, v13, v10
	s_waitcnt lgkmcnt(0)
	v_add_f32_e32 v14, v10, v14
	v_cndmask_b32_e64 v10, v14, v10, s[16:17]
	v_add_u32_e32 v14, -16, v216
	v_cmp_lt_i32_e32 vcc, v14, v8
	s_nop 1
	v_cndmask_b32_e32 v14, v14, v216, vcc
	v_lshlrev_b32_e32 v14, 2, v14
	ds_bpermute_b32 v15, v14, v10
	s_waitcnt lgkmcnt(0)
	v_add_f32_e32 v15, v10, v15
	v_cndmask_b32_e64 v10, v15, v10, s[68:69]
	v_subrev_u32_e32 v15, 32, v216
	v_cmp_lt_i32_e32 vcc, v15, v8
	s_nop 1
	v_cndmask_b32_e32 v8, v15, v216, vcc
	v_lshlrev_b32_e32 v8, 2, v8
	ds_bpermute_b32 v15, v8, v10
	s_waitcnt lgkmcnt(0)
	v_add_f32_e32 v15, v10, v15
	v_cndmask_b32_e64 v15, v15, v10, s[18:19]
	v_sub_f32_e32 v10, v38, v15
	ds_bpermute_b32 v9, v9, v10
	s_waitcnt lgkmcnt(0)
	v_max_f32_e32 v9, v9, v9
	v_max_f32_e32 v9, v10, v9
	v_cndmask_b32_e64 v9, v9, v10, s[48:49]
	ds_bpermute_b32 v11, v11, v9
	s_waitcnt lgkmcnt(0)
	v_max_f32_e32 v11, v11, v11
	v_max_f32_e32 v11, v9, v11
	v_cndmask_b32_e64 v9, v11, v9, s[12:13]
	ds_bpermute_b32 v11, v12, v9
	s_waitcnt lgkmcnt(0)
	v_max_f32_e32 v11, v11, v11
	v_max_f32_e32 v11, v9, v11
	v_cndmask_b32_e64 v9, v11, v9, s[14:15]
	ds_bpermute_b32 v11, v13, v9
	s_waitcnt lgkmcnt(0)
	v_max_f32_e32 v11, v11, v11
	v_max_f32_e32 v11, v9, v11
	v_cndmask_b32_e64 v9, v11, v9, s[16:17]
	ds_bpermute_b32 v11, v14, v9
	s_waitcnt lgkmcnt(0)
	v_max_f32_e32 v11, v11, v11
	v_max_f32_e32 v11, v9, v11
	v_cndmask_b32_e64 v9, v11, v9, s[68:69]
	ds_bpermute_b32 v8, v8, v9
	v_max_f32_e32 v11, v9, v9
	s_waitcnt lgkmcnt(0)
	v_max_f32_e32 v8, v8, v8
	v_max_f32_e32 v8, v11, v8
	v_cndmask_b32_e64 v9, v8, v9, s[18:19]
	v_bfrev_b32_e32 v8, 0.5
	v_lshl_or_b32 v11, v216, 2, v8
	ds_bpermute_b32 v8, v11, v15
	ds_bpermute_b32 v11, v11, v9
	s_waitcnt lgkmcnt(0)
	v_pk_add_f32 v[10:11], v[10:11], v[8:9] op_sel_hi:[1,0]
	s_nop 0
	v_sub_f32_e32 v9, v10, v11
	v_mul_f32_e32 v9, 0x3fb8aa3b, v9
	v_exp_f32_e32 v9, v9
	ds_write_b32 v163, v9
	s_and_saveexec_b64 s[12:13], s[48:49]
	s_cbranch_execz .LBB0_569
	s_ashr_i32 s9, s8, 31
	s_lshl_b64 s[8:9], s[8:9], 2
	s_add_u32 s14, s67, s8
	v_readlane_b32 s15, v251, 51
	s_addc_u32 s15, s15, s9
	s_add_u32 s8, s34, s8
	v_readlane_b32 s16, v251, 52
	s_addc_u32 s9, s16, s9
	s_nop 0
	global_store_dword v181, v11, s[14:15]
	global_store_dword v181, v8, s[8:9]

.LBB0_570:
	s_waitcnt lgkmcnt(0)
	s_barrier
	ds_read_b64_tr_b16 v[28:29], v179 offset:17408
	ds_read_b64_tr_b16 v[30:31], v179 offset:18496
	ds_read_b128 v[32:35], v164
	ds_read_b128 v[36:39], v164 offset:16
	ds_read_b64_tr_b16 v[40:41], v179 offset:26112
	ds_read_b64_tr_b16 v[42:43], v179 offset:27200
	ds_read_b128 v[44:47], v164 offset:128
	ds_read_b128 v[48:51], v164 offset:144
	ds_read_b64_tr_b16 v[52:53], v190 offset:34816
	ds_read_b64_tr_b16 v[54:55], v190 offset:36032
	ds_read_b64_tr_b16 v[56:57], v190 offset:44544
	ds_read_b64_tr_b16 v[58:59], v190 offset:45760
	ds_read_b64_tr_b16 v[60:61], v190 offset:34848
	ds_read_b64_tr_b16 v[62:63], v190 offset:36064
	s_waitcnt lgkmcnt(13)
	ds_read_b64_tr_b16 v[64:65], v190 offset:44576
	s_waitcnt lgkmcnt(13)
	ds_read_b64_tr_b16 v[66:67], v190 offset:45792
	s_waitcnt lgkmcnt(13)
	ds_read_b64_tr_b16 v[68:69], v190 offset:34880
	s_waitcnt lgkmcnt(13)
	ds_read_b64_tr_b16 v[70:71], v190 offset:36096
	s_waitcnt lgkmcnt(13)
	ds_read_b64_tr_b16 v[72:73], v190 offset:44608
	s_waitcnt lgkmcnt(13)
	ds_read_b64_tr_b16 v[74:75], v190 offset:45824
	s_waitcnt lgkmcnt(13)
	ds_read_b64_tr_b16 v[76:77], v190 offset:34912
	s_waitcnt lgkmcnt(13)
	ds_read_b64_tr_b16 v[78:79], v190 offset:36128
	s_waitcnt lgkmcnt(13)
	ds_read_b64_tr_b16 v[88:89], v190 offset:44640
	s_waitcnt lgkmcnt(13)
	ds_read_b64_tr_b16 v[90:91], v190 offset:45856
	s_waitcnt lgkmcnt(13)
	ds_read_b64_tr_b16 v[132:133], v190 offset:34944
	s_waitcnt lgkmcnt(13)
	ds_read_b64_tr_b16 v[134:135], v190 offset:36160
	s_waitcnt lgkmcnt(13)
	ds_read_b64_tr_b16 v[182:183], v190 offset:44672
	s_waitcnt lgkmcnt(13)
	ds_read_b64_tr_b16 v[184:185], v190 offset:45888
	s_waitcnt lgkmcnt(13)
	ds_read_b64_tr_b16 v[192:193], v190 offset:34976
	s_waitcnt lgkmcnt(13)
	ds_read_b64_tr_b16 v[194:195], v190 offset:36192
	s_waitcnt lgkmcnt(13)
	ds_read_b64_tr_b16 v[196:197], v190 offset:44704
	s_waitcnt lgkmcnt(13)
	ds_read_b64_tr_b16 v[198:199], v190 offset:45920
	s_waitcnt lgkmcnt(13)
	ds_read_b64_tr_b16 v[200:201], v190 offset:35008
	s_waitcnt lgkmcnt(13)
	ds_read_b64_tr_b16 v[202:203], v190 offset:36224
	s_waitcnt lgkmcnt(13)
	ds_read_b64_tr_b16 v[204:205], v190 offset:44736
	s_waitcnt lgkmcnt(13)
	ds_read_b64_tr_b16 v[206:207], v190 offset:45952
	s_waitcnt lgkmcnt(13)
	ds_read_b64_tr_b16 v[208:209], v190 offset:35040
	s_waitcnt lgkmcnt(13)
	ds_read_b64_tr_b16 v[210:211], v190 offset:36256
	s_waitcnt lgkmcnt(13)
	ds_read_b64_tr_b16 v[218:219], v190 offset:44768
	s_waitcnt lgkmcnt(13)
	ds_read_b64_tr_b16 v[220:221], v190 offset:45984
	s_waitcnt lgkmcnt(13)
	ds_read_b64_tr_b16 v[224:225], v190 offset:35072
	s_waitcnt lgkmcnt(13)
	ds_read_b64_tr_b16 v[226:227], v190 offset:36288
	s_nop 0
	s_nop 0
	s_nop 0
	s_nop 0
	v_readlane_b32 s72, v251, 4
	s_nop 0
	v_lshlrev_b32_e32 v20, 16, v28
	v_and_b32_e32 v21, 0xffff0000, v28
	s_nop 0
	v_pk_mul_f32 v[8:9], v[32:33], v[20:21]
	s_lshl_b64 s[8:9], s[26:27], 23
	v_cvt_pk_bf16_f32 v12, v8, v9
	v_lshlrev_b32_e32 v8, 16, v29
	v_and_b32_e32 v9, 0xffff0000, v29
	v_pk_mul_f32 v[8:9], v[34:35], v[8:9]
	v_readlane_b32 s86, v251, 18
	v_cvt_pk_bf16_f32 v13, v8, v9
	v_lshlrev_b32_e32 v8, 16, v30
	v_and_b32_e32 v9, 0xffff0000, v30
	s_nop 0
	v_pk_mul_f32 v[8:9], v[36:37], v[8:9]
	v_readlane_b32 s87, v251, 19
	v_cvt_pk_bf16_f32 v14, v8, v9
	v_lshlrev_b32_e32 v8, 16, v31
	v_and_b32_e32 v9, 0xffff0000, v31
	v_pk_mul_f32 v[8:9], v[38:39], v[8:9]
	s_add_u32 s8, s86, s8
	v_cvt_pk_bf16_f32 v15, v8, v9
	s_nop 0
	s_nop 0
	s_nop 0
	s_nop 0
	s_addc_u32 s9, s87, s9
	s_nop 0
	v_lshlrev_b32_e32 v24, 16, v40
	v_and_b32_e32 v25, 0xffff0000, v40
	v_lshlrev_b32_e32 v20, 16, v41
	v_and_b32_e32 v21, 0xffff0000, v41
	s_nop 0
	v_pk_mul_f32 v[8:9], v[44:45], v[24:25]
	v_pk_mul_f32 v[10:11], v[46:47], v[20:21]
	v_cvt_pk_bf16_f32 v8, v8, v9
	v_cvt_pk_bf16_f32 v9, v10, v11
	v_lshlrev_b32_e32 v10, 16, v42
	v_and_b32_e32 v11, 0xffff0000, v42
	s_nop 0
	v_pk_mul_f32 v[10:11], v[48:49], v[10:11]
	v_lshlrev_b32_e32 v16, 16, v43
	v_and_b32_e32 v17, 0xffff0000, v43
	v_pk_mul_f32 v[16:17], v[50:51], v[16:17]
	v_cvt_pk_bf16_f32 v10, v10, v11
	v_cvt_pk_bf16_f32 v11, v16, v17
	s_nop 0
	s_nop 0
	s_nop 0
	s_nop 0
	s_nop 0
	v_mfma_f32_16x16x32_bf16 v[16:19], v[12:15], v[52:55], 0
	s_and_b32 s12, s65, 0x7f
	s_mul_i32 s12, s12, 0x9000
	s_add_u32 s12, s8, s12
	s_addc_u32 s13, s9, 0
	s_lshl_b64 s[8:9], s[10:11], 1
	s_nop 0
	v_mfma_f32_16x16x32_bf16 v[16:19], v[8:11], v[56:59], v[16:19]
	s_add_u32 s8, s12, s8
	s_addc_u32 s9, s13, s9
	v_lshlrev_b32_e32 v180, 1, v102
	v_lshl_add_u64 v[24:25], s[8:9], 0, v[180:181]
	v_mov_b32_e32 v131, v181
	s_nop 2
	v_cvt_pk_bf16_f32 v20, v16, v17
	v_cvt_pk_bf16_f32 v21, v18, v19
	v_lshl_add_u64 v[16:17], v[24:25], 0, v[130:131]
	global_store_dwordx2 v[16:17], v[20:21], off
	s_nop 0
	s_nop 0
	s_nop 0
	s_nop 0
	s_nop 0
	v_mfma_f32_16x16x32_bf16 v[18:21], v[12:15], v[60:63], 0
	s_movk_i32 s8, 0x2000
	v_add_co_u32_e32 v26, vcc, s8, v16
	s_nop 0
	v_mfma_f32_16x16x32_bf16 v[18:21], v[8:11], v[64:67], v[18:21]
	v_addc_co_u32_e32 v27, vcc, 0, v17, vcc
	s_movk_i32 s8, 0x4000
	v_readlane_b32 s84, v251, 16
	v_readlane_b32 s85, v251, 17
	s_nop 3
	v_cvt_pk_bf16_f32 v18, v18, v19
	v_cvt_pk_bf16_f32 v19, v20, v21
	global_store_dwordx2 v[26:27], v[18:19], off offset:-4096
	s_nop 0
	s_nop 0
	s_nop 0
	s_nop 0
	s_nop 0
	v_mfma_f32_16x16x32_bf16 v[18:21], v[12:15], v[68:71], 0
	v_readlane_b32 s84, v254, 37
	v_readlane_b32 s86, v254, 39
	v_readlane_b32 s85, v254, 38
	s_nop 0
	v_mfma_f32_16x16x32_bf16 v[18:21], v[8:11], v[72:75], v[18:21]
	v_readlane_b32 s87, v254, 40
	v_readlane_b32 s73, v251, 5
	v_readlane_b32 s74, v251, 6
	v_readlane_b32 s75, v251, 7
	v_readlane_b32 s76, v251, 8
	s_nop 2
	v_cvt_pk_bf16_f32 v18, v18, v19
	v_cvt_pk_bf16_f32 v19, v20, v21
	global_store_dwordx2 v[26:27], v[18:19], off
	s_nop 0
	s_nop 0
	s_nop 0
	s_nop 0
	s_nop 0
	v_mfma_f32_16x16x32_bf16 v[18:21], v[12:15], v[76:79], 0
	v_add_co_u32_e32 v26, vcc, s8, v16
	s_movk_i32 s8, 0x6000
	s_nop 0
	v_mfma_f32_16x16x32_bf16 v[18:21], v[8:11], v[88:91], v[18:21]
	v_addc_co_u32_e32 v27, vcc, 0, v17, vcc
	v_readlane_b32 s77, v251, 9
	v_readlane_b32 s78, v251, 10
	v_readlane_b32 s79, v251, 11
	s_nop 3
	v_cvt_pk_bf16_f32 v18, v18, v19
	v_cvt_pk_bf16_f32 v19, v20, v21
	global_store_dwordx2 v[26:27], v[18:19], off offset:-4096
	s_nop 0
	s_nop 0
	s_nop 0
	s_nop 0
	s_nop 0
	v_mfma_f32_16x16x32_bf16 v[18:21], v[12:15], v[132:135], 0
	v_readlane_b32 s80, v251, 12
	v_readlane_b32 s81, v251, 13
	v_readlane_b32 s82, v251, 14
	s_nop 0
	v_mfma_f32_16x16x32_bf16 v[18:21], v[8:11], v[182:185], v[18:21]
	v_readlane_b32 s83, v251, 15
	s_nop 6
	v_cvt_pk_bf16_f32 v18, v18, v19
	v_cvt_pk_bf16_f32 v19, v20, v21
	global_store_dwordx2 v[26:27], v[18:19], off
	s_nop 0
	s_nop 0
	s_nop 0
	s_nop 0
	s_nop 0
	s_waitcnt lgkmcnt(12)
	v_mfma_f32_16x16x32_bf16 v[18:21], v[12:15], v[192:195], 0
	v_add_co_u32_e32 v26, vcc, s8, v16
	s_movk_i32 s8, 0x7000
	s_nop 0
	s_waitcnt lgkmcnt(10)
	v_mfma_f32_16x16x32_bf16 v[18:21], v[8:11], v[196:199], v[18:21]
	v_addc_co_u32_e32 v27, vcc, 0, v17, vcc
	s_nop 6
	v_cvt_pk_bf16_f32 v18, v18, v19
	v_cvt_pk_bf16_f32 v19, v20, v21
	global_store_dwordx2 v[26:27], v[18:19], off offset:-4096
	s_nop 0
	s_nop 0
	s_nop 0
	s_nop 0
	s_nop 0
	s_waitcnt lgkmcnt(8)
	v_mfma_f32_16x16x32_bf16 v[18:21], v[12:15], v[200:203], 0
	s_nop 0
	s_waitcnt lgkmcnt(6)
	v_mfma_f32_16x16x32_bf16 v[18:21], v[8:11], v[204:207], v[18:21]
	s_nop 7
	v_cvt_pk_bf16_f32 v18, v18, v19
	v_cvt_pk_bf16_f32 v19, v20, v21
	global_store_dwordx2 v[26:27], v[18:19], off
	s_nop 0
	s_nop 0
	s_nop 0
	s_nop 0
	s_nop 0
	s_waitcnt lgkmcnt(4)
	v_mfma_f32_16x16x32_bf16 v[18:21], v[12:15], v[208:211], 0
	s_nop 0
	s_waitcnt lgkmcnt(2)
	v_mfma_f32_16x16x32_bf16 v[18:21], v[8:11], v[218:221], v[18:21]
	s_nop 7
	v_cvt_pk_bf16_f32 v18, v18, v19
	v_cvt_pk_bf16_f32 v19, v20, v21
	v_add_co_u32_e32 v20, vcc, s8, v16
	s_nop 1
	v_addc_co_u32_e32 v21, vcc, 0, v17, vcc
	global_store_dwordx2 v[20:21], v[18:19], off
	s_nop 0
	s_nop 0
	s_nop 0
	s_waitcnt lgkmcnt(0)
	v_mfma_f32_16x16x32_bf16 v[12:15], v[12:15], v[224:227], 0
	ds_read_b64_tr_b16 v[18:19], v190 offset:44800
	ds_read_b64_tr_b16 v[20:21], v190 offset:46016
	s_nop 0
	s_waitcnt lgkmcnt(0)
	v_mfma_f32_16x16x32_bf16 v[8:11], v[8:11], v[18:21], v[12:15]
	s_nop 7
	v_cvt_pk_bf16_f32 v8, v8, v9
	v_cvt_pk_bf16_f32 v9, v10, v11
	v_add_co_u32_e32 v10, vcc, 0x8000, v16
	s_nop 1
	v_addc_co_u32_e32 v11, vcc, 0, v17, vcc
	global_store_dwordx2 v[10:11], v[8:9], off
	s_nop 0
	s_waitcnt lgkmcnt(0)
	s_barrier
